# dftfin streaming loops: loop-invariant pointers loaded once in the preheader instead of s_load_dwordx16 + wait every iteration; downstream code kept at its previous 64-byte placement
# baseline (speedup 1.0000x reference)
; DI int tid_() { int t = threadIdx.x; asm volatile("" : "+v"(t)); return t; }
; DI void phase_dftfin(const GroupP& g, int vb) {
;   const int tid = tid_();
;   const int H = g.L >> 1, Hp = g.Hp, L = g.L, Lp = g.Lp;
;   const float* P = dft_part(g, 0);
;   const float* Q = dft_part(g, 1);
;   const int total = g.B * (H + 1) * 128;
;   for (int i = vb * NTHR + tid; i < total; i += gridDim.x * NTHR) {
; __global__ void __launch_bounds__(NTHR, 2) mega(Params p_unused, int ph_lo, int ph_hi) {
;     ...
;     p.grp[0].uf = kp->grp[0].uf;
;     p.grp[0].cq = kp->grp[0].cq;
;     p.grp[0].ckv = kp->grp[0].ckv;
;     p.grp[0].kr = kp->grp[0].kr;
;     p.grp[0].qd = kp->grp[0].qd;
;     p.grp[0].kd = kp->grp[0].kd;
;     p.grp[0].vdt = kp->grp[0].vdt;
;     p.grp[0].g = kp->grp[0].g;
;     p.grp[0].q = kp->grp[0].q;
;     p.grp[0].abt = kp->grp[0].abt;
;     p.grp[0].fm = kp->grp[0].fm;
;     p.grp[0].h1b = kp->grp[0].h1b;
;     p.grp[1].x = kp->grp[1].x;
;     p.grp[1].out = kp->grp[1].out;
;     p.grp[1].B = kp->grp[1].B;
;     p.grp[1].L = kp->grp[1].L;
;     p.grp[1].Lp = kp->grp[1].Lp;
;     p.grp[1].T = kp->grp[1].T;
;     p.grp[1].seq0 = kp->grp[1].seq0;
;     p.grp[1].Hp = kp->grp[1].Hp;
;     p.grp[1].xb = kp->grp[1].xb;
;     p.grp[1].uf = kp->grp[1].uf;
;     p.grp[1].cq = kp->grp[1].cq;
;     p.grp[1].ckv = kp->grp[1].ckv;
;     p.grp[1].kr = kp->grp[1].kr;
;     p.grp[1].qd = kp->grp[1].qd;
;     p.grp[1].kd = kp->grp[1].kd;
;     p.grp[1].vdt = kp->grp[1].vdt;
;     p.grp[1].g = kp->grp[1].g;
;     p.grp[1].q = kp->grp[1].q;
;     p.grp[1].abt = kp->grp[1].abt;
;     p.grp[1].fm = kp->grp[1].fm;
;     p.grp[1].h1b = kp->grp[1].h1b;
;     p.meta = kp->meta;
;     p.rel_bias = kp->rel_bias;
;     p.final_norm = kp->final_norm;
;     p.norm_w = kp->norm_w;
;     p.w_in = kp->w_in;
;     p.w_fmix = kp->w_fmix;
;     p.q_norm = kp->q_norm;
;     p.w_uq = kp->w_uq;
;     p.kv_norm = kp->kv_norm;
;     p.w_ukv = kp->w_ukv;
;     p.lq1 = kp->lq1;
;     p.lk1 = kp->lk1;
;     p.lq2 = kp->lq2;
;     p.lk2 = kp->lk2;
;     p.diff_norm = kp->diff_norm;
;     p.w_o = kp->w_o;
;     p.winT = kp->winT;
;     p.wuqT = kp->wuqT;
;     p.wukvT = kp->wukvT;
;     p.woT = kp->woT;
;     p.mfT = kp->mfT;
;     p.rope = kp->rope;
;     p.lam = kp->lam;
;     p.hmeta = kp->hmeta;
;     p.ctr = kp->ctr;
;     p.bar = kp->bar;
;     p.rowsq = kp->rowsq;
.LBB0_11:
	s_load_dwordx2 s[42:43], s[28:29], 0x20
	s_load_dwordx8 s[4:11], s[28:29], 0x68
	s_waitcnt lgkmcnt(0)
	v_writelane_b32 v253, s4, 47
	s_nop 1
	v_writelane_b32 v253, s5, 48
	v_writelane_b32 v253, s6, 49
	v_writelane_b32 v253, s7, 50
	v_writelane_b32 v253, s8, 51
	v_writelane_b32 v253, s9, 52
	v_writelane_b32 v253, s10, 53
	v_writelane_b32 v253, s11, 54
	s_load_dwordx4 s[4:7], s[28:29], 0x88
	s_waitcnt lgkmcnt(0)
	v_writelane_b32 v253, s4, 55
	s_nop 1
	v_writelane_b32 v253, s5, 56
	v_writelane_b32 v253, s6, 57
	v_writelane_b32 v253, s7, 58
	s_load_dwordx2 s[4:5], s[28:29], 0xb0
	s_waitcnt lgkmcnt(0)
	v_writelane_b32 v253, s4, 59
	s_nop 1
	v_writelane_b32 v253, s5, 60
	s_load_dwordx16 s[4:19], s[28:29], 0x28
	s_waitcnt lgkmcnt(0)
	v_writelane_b32 v253, s4, 61
	s_nop 1
	v_writelane_b32 v254, s7, 0
	v_writelane_b32 v254, s8, 1
	v_writelane_b32 v254, s9, 2
	v_writelane_b32 v254, s10, 3
	v_writelane_b32 v254, s11, 4
	v_writelane_b32 v254, s12, 5
	v_writelane_b32 v254, s13, 6
	v_writelane_b32 v254, s14, 7
	v_writelane_b32 v254, s15, 8
	v_writelane_b32 v254, s16, 9
	v_writelane_b32 v254, s17, 10
	v_writelane_b32 v253, s5, 62
	v_writelane_b32 v254, s18, 11
	v_writelane_b32 v253, s6, 63
	v_writelane_b32 v254, s19, 12
	s_load_dwordx16 s[4:19], s[28:29], 0xb8
	s_waitcnt lgkmcnt(0)
	v_writelane_b32 v254, s4, 13
	s_nop 1
	v_writelane_b32 v254, s5, 14
	v_writelane_b32 v254, s6, 15
	v_writelane_b32 v254, s7, 16
	v_writelane_b32 v254, s8, 17
	v_writelane_b32 v254, s9, 18
	v_writelane_b32 v254, s10, 19
	v_writelane_b32 v254, s11, 20
	v_writelane_b32 v254, s12, 21
	v_writelane_b32 v254, s13, 22
	v_writelane_b32 v254, s14, 23
	v_writelane_b32 v254, s15, 24
	v_writelane_b32 v254, s16, 25
	v_writelane_b32 v254, s17, 26
	v_writelane_b32 v254, s18, 27
	v_writelane_b32 v254, s19, 28
	s_load_dwordx16 s[4:19], s[28:29], 0x178
	s_waitcnt lgkmcnt(0)
	v_writelane_b32 v253, s4, 23
	s_nop 1
	v_writelane_b32 v253, s5, 24
	v_writelane_b32 v253, s6, 25
	v_writelane_b32 v253, s7, 26
	v_writelane_b32 v253, s8, 27
	v_writelane_b32 v253, s9, 28
	v_writelane_b32 v253, s10, 29
	v_writelane_b32 v253, s11, 30
	v_writelane_b32 v253, s12, 31
	v_writelane_b32 v253, s13, 32
	v_writelane_b32 v253, s14, 33
	v_writelane_b32 v253, s15, 34
	v_writelane_b32 v253, s16, 35
	v_writelane_b32 v253, s17, 36
	v_writelane_b32 v253, s18, 37
	v_writelane_b32 v253, s19, 38
	v_readlane_b32 s8, v252, 4
	s_cmp_lt_i32 s8, 6
	s_cselect_b64 s[4:5], -1, 0
	s_add_i32 s6, s8, -5
	v_writelane_b32 v254, s4, 29
	s_cmp_gt_i32 s8, 5
	v_readlane_b32 s9, v252, 5
	v_writelane_b32 v254, s5, 30
	s_cselect_b64 s[4:5], -1, 0
	v_writelane_b32 v254, s4, 31
	s_nop 1
	v_writelane_b32 v254, s5, 32
	s_and_b64 s[4:5], s[4:5], exec
	s_cselect_b32 s6, s6, s8
	v_readlane_b32 s4, v252, 45
	v_writelane_b32 v254, s6, 33
	s_cmp_lt_i32 s6, 2
	s_mov_b64 s[6:7], 0
	v_readlane_b32 s5, v252, 46
	v_writelane_b32 v254, s6, 34
	s_load_dword s72, s[4:5], 0x0
	s_mov_b64 s[4:5], -1
	v_writelane_b32 v254, s7, 35
	v_writelane_b32 v254, s28, 36
	s_nop 1
	v_writelane_b32 v254, s29, 37
	v_writelane_b32 v254, s42, 38
	s_nop 1
	v_writelane_b32 v254, s43, 39
	s_cbranch_scc1 .LBB0_446
	v_readlane_b32 s4, v254, 33
	s_cmp_gt_i32 s4, 2
	s_movk_i32 s68, 0x80
	s_waitcnt lgkmcnt(0)
	v_writelane_b32 v254, s72, 40
	s_cbranch_scc0 .LBB0_20
	s_cmp_gt_i32 s4, 3
	s_cbranch_scc0 .LBB0_21
	s_cmp_eq_u32 s4, 4
	s_mov_b64 s[4:5], -1
	s_movk_i32 s92, 0x101
	s_movk_i32 s69, 0x5b
	s_mov_b32 s70, 0x3fb8aa3b
	s_movk_i32 s71, 0x110
	s_movk_i32 s93, 0x4000
	s_cbranch_scc0 .LBB0_28
	s_ashr_i32 s12, s1, 1
	s_add_i32 s13, s12, 1
	s_mul_i32 s4, s13, s0
	v_mov_b32_e32 v0, v200
	s_lshl_b32 s14, s4, 7
	v_readlane_b32 s4, v252, 22
	s_nop 1
	v_add_u32_e32 v10, s4, v0
	v_cmp_gt_i32_e32 vcc, s14, v10
	s_and_saveexec_b64 s[4:5], vcc
	s_cbranch_execz .LBB0_22
	v_readlane_b32 s8, v254, 36
	v_readlane_b32 s9, v254, 37
	s_load_dwordx16 s[16:31], s[8:9], 0xb8
	v_readlane_b32 s10, v253, 59
	v_readlane_b32 s11, v253, 60
	s_mul_hi_i32 s7, s0, s11
	s_mul_i32 s6, s0, s11
	s_lshl_b64 s[6:7], s[6:7], 11
	s_waitcnt lgkmcnt(0)
	s_add_u32 s6, s20, s6
	s_addc_u32 s7, s21, s7
	s_abs_i32 s15, s13
	v_cvt_f32_u32_e32 v1, s15
	v_readlane_b32 s8, v252, 21
	v_readlane_b32 s28, v254, 36
	v_readlane_b32 s29, v254, 37
	v_rcp_iflag_f32_e32 v1, v1
	v_lshl_add_u32 v11, v0, 2, s8
	s_sub_i32 s8, 0, s15
	s_mov_b32 s16, s11
	v_mul_f32_e32 v0, 0x4f7ffffe, v1
	v_cvt_u32_f32_e32 v0, v0
	s_lshl_b32 s17, s72, 8
	s_ashr_i32 s18, s13, 31
	s_lshl_b32 s19, s72, 10
	v_mul_lo_u32 v1, s8, v0
	v_mul_hi_u32 v1, v0, v1
	v_add_u32_e32 v12, v0, v1
	s_mov_b64 s[10:11], 0
	s_load_dwordx2 s[56:57], s[28:29], 0xc8
	s_load_dwordx2 s[54:55], s[28:29], 0xc0
	s_load_dwordx2 s[36:37], s[28:29], 0xf8
	s_load_dwordx2 s[38:39], s[28:29], 0xc0
	s_waitcnt lgkmcnt(0)
	s_branch .LBB0_18

; DI float bf_lo(unsigned u) { return __uint_as_float(u << 16); }
; DI float bf_hi(unsigned u) { return __uint_as_float(u & 0xffff0000u); }
; DI void phase_dftfin(const GroupP& g, int vb) {
;     ...
;   for (int i = vb * NTHR + tid; i < total; i += gridDim.x * NTHR) {
;     const int c = i & 127, rk = i >> 7;
;     const int b = rk / (H + 1), k = rk - b * (H + 1);
;     const size_t src = ((size_t)b * Hp + k) * 512 + c * 4;
;     const float4 pv = *(const float4*)(P + src);
;     const float4 qv = *(const float4*)(Q + src);
;     const long row1 = (long)b * Lp + k;
;     const u32x2 g1 = *(const u32x2*)(g.g + row1 * 2048 + c * 4);
;     store_bf4(g.uf + row1 * 512 + c * 4, (pv.x + qv.x) * bf_lo(g1[0]), (pv.y + qv.y) * bf_hi(g1[0]), (pv.z + qv.z) * bf_lo(g1[1]),
;               (pv.w + qv.w) * bf_hi(g1[1]));
;     if (k >= 1 && k < H) {
;       const long row2 = (long)b * Lp + (L - k);
;       const u32x2 g2 = *(const u32x2*)(g.g + row2 * 2048 + c * 4);
;       store_bf4(g.uf + row2 * 512 + c * 4, (pv.x - qv.x) * bf_lo(g2[0]), (pv.y - qv.y) * bf_hi(g2[0]), (pv.z - qv.z) * bf_lo(g2[1]),
;                 (pv.w - qv.w) * bf_hi(g2[1]));
;     }
;   }
.LBB0_18:
	v_ashrrev_i32_e32 v0, 7, v10
	v_sub_u32_e32 v2, 0, v0
	v_max_i32_e32 v2, v0, v2
	v_mul_hi_u32 v3, v2, v12
	v_mul_lo_u32 v4, v3, s15
	v_sub_u32_e32 v2, v2, v4
	v_cmp_le_u32_e32 vcc, s15, v2
	v_add_u32_e32 v4, 1, v3
	v_ashrrev_i32_e32 v1, 31, v10
	v_cndmask_b32_e32 v3, v3, v4, vcc
	v_subrev_u32_e32 v4, s15, v2
	v_cndmask_b32_e32 v2, v2, v4, vcc
	v_cmp_le_u32_e32 vcc, s15, v2
	v_add_u32_e32 v2, 1, v3
	v_xor_b32_e32 v1, s18, v1
	v_cndmask_b32_e32 v2, v3, v2, vcc
	v_xor_b32_e32 v2, v2, v1
	v_sub_u32_e32 v13, v2, v1
	v_mul_lo_u32 v1, v13, s13
	v_sub_u32_e32 v8, v0, v1
	v_ashrrev_i32_e32 v9, 31, v8
	v_mad_i64_i32 v[0:1], s[8:9], v13, s16, v[8:9]
	v_and_b32_e32 v18, 0x1fc, v11
	v_lshlrev_b64 v[0:1], 11, v[0:1]
	v_lshl_or_b32 v0, v18, 2, v0
	s_waitcnt lgkmcnt(0)
	v_lshl_add_u64 v[2:3], s[56:57], 0, v[0:1]
	v_lshl_add_u64 v[4:5], s[6:7], 0, v[0:1]
	global_load_dwordx4 v[0:3], v[2:3], off
	s_nop 0
	global_load_dwordx4 v[4:7], v[4:5], off
	v_mad_i64_i32 v[14:15], s[8:9], v13, s2, v[8:9]
	v_lshlrev_b64 v[16:17], 12, v[14:15]
	v_lshlrev_b32_e32 v184, 1, v18
	s_waitcnt lgkmcnt(0)
	v_lshl_add_u64 v[16:17], s[36:37], 0, v[16:17]
	v_lshl_add_u64 v[16:17], v[16:17], 0, v[184:185]
	global_load_dwordx2 v[16:17], v[16:17], off
	v_lshlrev_b64 v[14:15], 10, v[14:15]
	v_lshl_add_u64 v[14:15], s[54:55], 0, v[14:15]
	v_cmp_lt_i32_e32 vcc, 0, v8
	v_cmp_gt_i32_e64 s[8:9], s12, v8
	v_lshl_add_u64 v[14:15], v[14:15], 0, v[184:185]
	s_and_b64 s[20:21], vcc, s[8:9]
	s_waitcnt vmcnt(1)
	v_pk_add_f32 v[18:19], v[0:1], v[4:5]
	s_waitcnt vmcnt(0)
	v_lshlrev_b32_e32 v20, 16, v16
	v_and_b32_e32 v21, 0xffff0000, v16
	v_pk_mul_f32 v[18:19], v[18:19], v[20:21]
	v_pk_add_f32 v[20:21], v[2:3], v[6:7]
	v_lshlrev_b32_e32 v16, 16, v17
	v_and_b32_e32 v17, 0xffff0000, v17
	v_pk_mul_f32 v[16:17], v[20:21], v[16:17]
	v_cvt_pk_bf16_f32 v18, v18, v19
	v_cvt_pk_bf16_f32 v19, v16, v17
	global_store_dwordx2 v[14:15], v[18:19], off
	s_and_saveexec_b64 s[8:9], s[20:21]
	s_cbranch_execz .LBB0_17
	v_sub_u32_e32 v8, s1, v8
	v_mad_i64_i32 v[14:15], s[20:21], v13, s2, 0
	v_ashrrev_i32_e32 v9, 31, v8
	v_lshl_add_u64 v[8:9], v[14:15], 0, v[8:9]
	v_lshlrev_b64 v[14:15], 12, v[8:9]
	s_waitcnt lgkmcnt(0)
	v_lshl_add_u64 v[14:15], s[36:37], 0, v[14:15]
	v_lshl_add_u64 v[14:15], v[14:15], 0, v[184:185]
	global_load_dwordx2 v[14:15], v[14:15], off
	v_pk_add_f32 v[0:1], v[0:1], v[4:5] neg_lo:[0,1] neg_hi:[0,1]
	v_pk_add_f32 v[2:3], v[2:3], v[6:7] neg_lo:[0,1] neg_hi:[0,1]
	v_lshlrev_b64 v[4:5], 10, v[8:9]
	s_waitcnt lgkmcnt(0)
	v_lshl_add_u64 v[4:5], s[38:39], 0, v[4:5]
	v_lshl_add_u64 v[4:5], v[4:5], 0, v[184:185]
	s_waitcnt vmcnt(0)
	v_lshlrev_b32_e32 v6, 16, v14
	v_and_b32_e32 v7, 0xffff0000, v14
	v_lshlrev_b32_e32 v8, 16, v15
	v_and_b32_e32 v9, 0xffff0000, v15
	v_pk_mul_f32 v[0:1], v[0:1], v[6:7]
	v_pk_mul_f32 v[2:3], v[2:3], v[8:9]
	v_cvt_pk_bf16_f32 v0, v0, v1
	v_cvt_pk_bf16_f32 v1, v2, v3
	global_store_dwordx2 v[4:5], v[0:1], off
	s_branch .LBB0_17

; DI int tid_() { int t = threadIdx.x; asm volatile("" : "+v"(t)); return t; }
; DI float* dft_part(const GroupP& g, int part) { return (float*)g.cq + (size_t)part * g.B * g.Hp * 512; }
; DI void phase_dftfin(const GroupP& g, int vb) {
;   const int tid = tid_();
;   const int H = g.L >> 1, Hp = g.Hp, L = g.L, Lp = g.Lp;
;   const float* P = dft_part(g, 0);
;   const float* Q = dft_part(g, 1);
;   const int total = g.B * (H + 1) * 128;
;   for (int i = vb * NTHR + tid; i < total; i += gridDim.x * NTHR) {
.LBB0_22:
	s_or_b64 exec, exec, s[4:5]
	s_ashr_i32 s12, s81, 1
	s_add_i32 s13, s12, 1
	s_mul_i32 s4, s13, s80
	v_mov_b32_e32 v0, v200
	s_lshl_b32 s14, s4, 7
	v_readlane_b32 s4, v252, 22
	s_nop 1
	v_add_u32_e32 v10, s4, v0
	v_cmp_gt_i32_e32 vcc, s14, v10
	s_and_saveexec_b64 s[4:5], vcc
	s_cbranch_execz .LBB0_27
	v_readlane_b32 s8, v254, 36
	v_readlane_b32 s9, v254, 37
	s_load_dwordx16 s[16:31], s[8:9], 0x28
	v_readlane_b32 s10, v254, 38
	v_readlane_b32 s11, v254, 39
	s_mul_hi_i32 s7, s80, s11
	s_mul_i32 s6, s80, s11
	s_lshl_b64 s[6:7], s[6:7], 11
	s_waitcnt lgkmcnt(0)
	s_add_u32 s6, s20, s6
	s_addc_u32 s7, s21, s7
	s_abs_i32 s15, s13
	v_cvt_f32_u32_e32 v1, s15
	v_readlane_b32 s8, v252, 21
	v_readlane_b32 s28, v254, 36
	v_readlane_b32 s29, v254, 37
	v_rcp_iflag_f32_e32 v1, v1
	v_lshl_add_u32 v11, v0, 2, s8
	s_sub_i32 s8, 0, s15
	s_mov_b32 s16, s11
	v_mul_f32_e32 v0, 0x4f7ffffe, v1
	v_cvt_u32_f32_e32 v0, v0
	s_lshl_b32 s17, s72, 8
	s_ashr_i32 s18, s13, 31
	s_lshl_b32 s19, s72, 10
	v_mul_lo_u32 v1, s8, v0
	v_mul_hi_u32 v1, v0, v1
	v_add_u32_e32 v12, v0, v1
	s_mov_b64 s[10:11], 0
	s_load_dwordx2 s[38:39], s[28:29], 0x30
	s_load_dwordx2 s[40:41], s[28:29], 0x38
	s_waitcnt lgkmcnt(0)
	s_branch .LBB0_25
	s_nop 0
	s_nop 0
	s_nop 0
	s_nop 0
	s_nop 0
	s_nop 0
	s_nop 0
	s_nop 0
	s_nop 0
	s_nop 0
	s_nop 0
	s_nop 0
	s_nop 0
	s_nop 0

; DI float bf_lo(unsigned u) { return __uint_as_float(u << 16); }
; DI float bf_hi(unsigned u) { return __uint_as_float(u & 0xffff0000u); }
; DI void phase_dftfin(const GroupP& g, int vb) {
;     ...
;   for (int i = vb * NTHR + tid; i < total; i += gridDim.x * NTHR) {
;     const int c = i & 127, rk = i >> 7;
;     const int b = rk / (H + 1), k = rk - b * (H + 1);
;     const size_t src = ((size_t)b * Hp + k) * 512 + c * 4;
;     const float4 pv = *(const float4*)(P + src);
;     const float4 qv = *(const float4*)(Q + src);
;     const long row1 = (long)b * Lp + k;
;     const u32x2 g1 = *(const u32x2*)(g.g + row1 * 2048 + c * 4);
;     store_bf4(g.uf + row1 * 512 + c * 4, (pv.x + qv.x) * bf_lo(g1[0]), (pv.y + qv.y) * bf_hi(g1[0]), (pv.z + qv.z) * bf_lo(g1[1]),
;               (pv.w + qv.w) * bf_hi(g1[1]));
;     if (k >= 1 && k < H) {
;       const long row2 = (long)b * Lp + (L - k);
;       const u32x2 g2 = *(const u32x2*)(g.g + row2 * 2048 + c * 4);
;       store_bf4(g.uf + row2 * 512 + c * 4, (pv.x - qv.x) * bf_lo(g2[0]), (pv.y - qv.y) * bf_hi(g2[0]), (pv.z - qv.z) * bf_lo(g2[1]),
;                 (pv.w - qv.w) * bf_hi(g2[1]));
;     }
;   }
.LBB0_25:
	v_ashrrev_i32_e32 v0, 7, v10
	v_sub_u32_e32 v2, 0, v0
	v_max_i32_e32 v2, v0, v2
	v_mul_hi_u32 v3, v2, v12
	v_mul_lo_u32 v4, v3, s15
	v_sub_u32_e32 v2, v2, v4
	v_cmp_le_u32_e32 vcc, s15, v2
	v_add_u32_e32 v4, 1, v3
	v_ashrrev_i32_e32 v1, 31, v10
	v_cndmask_b32_e32 v3, v3, v4, vcc
	v_subrev_u32_e32 v4, s15, v2
	v_cndmask_b32_e32 v2, v2, v4, vcc
	v_cmp_le_u32_e32 vcc, s15, v2
	v_add_u32_e32 v2, 1, v3
	v_xor_b32_e32 v1, s18, v1
	v_cndmask_b32_e32 v2, v3, v2, vcc
	v_xor_b32_e32 v2, v2, v1
	v_sub_u32_e32 v13, v2, v1
	v_mul_lo_u32 v1, v13, s13
	v_sub_u32_e32 v8, v0, v1
	v_ashrrev_i32_e32 v9, 31, v8
	v_mad_i64_i32 v[0:1], s[8:9], v13, s16, v[8:9]
	v_mad_i64_i32 v[14:15], s[8:9], v13, s82, v[8:9]
	v_readlane_b32 s20, v253, 47
	v_and_b32_e32 v18, 0x1fc, v11
	v_lshlrev_b64 v[0:1], 11, v[0:1]
	v_lshlrev_b64 v[16:17], 12, v[14:15]
	v_readlane_b32 s21, v253, 48
	v_lshl_or_b32 v0, v18, 2, v0
	v_lshlrev_b32_e32 v184, 1, v18
	v_lshl_add_u64 v[16:17], s[20:21], 0, v[16:17]
	s_waitcnt lgkmcnt(0)
	v_lshl_add_u64 v[2:3], s[40:41], 0, v[0:1]
	v_lshl_add_u64 v[4:5], s[6:7], 0, v[0:1]
	v_lshl_add_u64 v[16:17], v[16:17], 0, v[184:185]
	global_load_dwordx4 v[0:3], v[2:3], off
	s_nop 0
	global_load_dwordx4 v[4:7], v[4:5], off
	v_lshlrev_b64 v[14:15], 10, v[14:15]
	global_load_dwordx2 v[16:17], v[16:17], off
	v_lshl_add_u64 v[14:15], s[38:39], 0, v[14:15]
	v_cmp_lt_i32_e32 vcc, 0, v8
	v_cmp_gt_i32_e64 s[8:9], s12, v8
	v_lshl_add_u64 v[14:15], v[14:15], 0, v[184:185]
	s_and_b64 s[20:21], vcc, s[8:9]
	v_readlane_b32 s22, v253, 49
	v_readlane_b32 s23, v253, 50
	v_readlane_b32 s24, v253, 51
	v_readlane_b32 s25, v253, 52
	v_readlane_b32 s26, v253, 53
	v_readlane_b32 s27, v253, 54
	s_waitcnt vmcnt(1)
	v_pk_add_f32 v[18:19], v[0:1], v[4:5]
	s_waitcnt vmcnt(0)
	v_lshlrev_b32_e32 v20, 16, v16
	v_and_b32_e32 v21, 0xffff0000, v16
	v_pk_mul_f32 v[18:19], v[18:19], v[20:21]
	v_pk_add_f32 v[20:21], v[2:3], v[6:7]
	v_lshlrev_b32_e32 v16, 16, v17
	v_and_b32_e32 v17, 0xffff0000, v17
	v_pk_mul_f32 v[16:17], v[20:21], v[16:17]
	v_cvt_pk_bf16_f32 v18, v18, v19
	v_cvt_pk_bf16_f32 v19, v16, v17
	global_store_dwordx2 v[14:15], v[18:19], off
	s_and_saveexec_b64 s[8:9], s[20:21]
	s_cbranch_execz .LBB0_24
	v_sub_u32_e32 v8, s81, v8
	v_mad_i64_i32 v[14:15], s[20:21], v13, s82, 0
	v_ashrrev_i32_e32 v9, 31, v8
	v_lshl_add_u64 v[8:9], v[14:15], 0, v[8:9]
	v_readlane_b32 s20, v253, 47
	v_lshlrev_b64 v[14:15], 12, v[8:9]
	v_readlane_b32 s21, v253, 48
	v_pk_add_f32 v[0:1], v[0:1], v[4:5] neg_lo:[0,1] neg_hi:[0,1]
	v_lshl_add_u64 v[14:15], s[20:21], 0, v[14:15]
	v_lshl_add_u64 v[14:15], v[14:15], 0, v[184:185]
	global_load_dwordx2 v[14:15], v[14:15], off
	v_pk_add_f32 v[2:3], v[2:3], v[6:7] neg_lo:[0,1] neg_hi:[0,1]
	v_lshlrev_b64 v[4:5], 10, v[8:9]
	s_waitcnt lgkmcnt(0)
	v_lshl_add_u64 v[4:5], s[38:39], 0, v[4:5]
	v_lshl_add_u64 v[4:5], v[4:5], 0, v[184:185]
	v_readlane_b32 s22, v253, 49
	v_readlane_b32 s23, v253, 50
	v_readlane_b32 s24, v253, 51
	v_readlane_b32 s25, v253, 52
	v_readlane_b32 s26, v253, 53
	v_readlane_b32 s27, v253, 54
	s_waitcnt vmcnt(0)
	v_lshlrev_b32_e32 v6, 16, v14
	v_and_b32_e32 v7, 0xffff0000, v14
	v_lshlrev_b32_e32 v8, 16, v15
	v_and_b32_e32 v9, 0xffff0000, v15
	v_pk_mul_f32 v[0:1], v[0:1], v[6:7]
	v_pk_mul_f32 v[2:3], v[2:3], v[8:9]
	v_cvt_pk_bf16_f32 v0, v0, v1
	v_cvt_pk_bf16_f32 v1, v2, v3
	global_store_dwordx2 v[4:5], v[0:1], off
	s_branch .LBB0_24
